# attention: fixed softmax reference in steady/band steps (QK-norm bounds logits), drop hipcc loop-top vmcnt(0)
# speedup vs baseline: 1.0260x; 1.0260x over previous
.LBB0_798:
	v_bfe_i32 v196, v132, 0, 1
	v_add_u32_e32 v197, s10, v219
	ds_read_b64_tr_b16 v[184:185], v197 offset:24576
	ds_read_b64_tr_b16 v[186:187], v197 offset:25088
	s_waitcnt lgkmcnt(9)
	v_mfma_f32_32x32x16_bf16 v[100:115], v[180:183], v[116:119], v[36:51]
	v_add_f32_e32 v84, v68, v69
	v_add_f32_e32 v84, v70, v84
	v_add_f32_e32 v84, v71, v84
	v_cvt_pk_bf16_f32 v68, v68, v69
	v_add_f32_e32 v84, v72, v84
	v_and_b32_e32 v148, v68, v196
	v_cvt_pk_bf16_f32 v68, v70, v71
	v_add_f32_e32 v84, v73, v84
	v_and_b32_e32 v149, v68, v196
	ds_read_b64_tr_b16 v[180:181], v197 offset:28672
	ds_read_b64_tr_b16 v[182:183], v197 offset:29184
	v_add_f32_e32 v68, v74, v84
	s_waitcnt lgkmcnt(10)
	v_mfma_f32_32x32x16_bf16 v[84:99], v[176:179], v[116:119], v[36:51]
	v_add_f32_e32 v68, v75, v68
	v_add_f32_e32 v68, v76, v68
	v_add_f32_e32 v136, v77, v68
	v_cvt_pk_bf16_f32 v68, v72, v73
	v_and_b32_e32 v150, v68, v196
	v_cvt_pk_bf16_f32 v68, v74, v75
	v_and_b32_e32 v151, v68, v196
	ds_read_b64_tr_b16 v[68:69], v197 offset:25600
	ds_read_b64_tr_b16 v[70:71], v197 offset:26112
	s_waitcnt lgkmcnt(11)
	v_mfma_f32_32x32x16_bf16 v[100:115], v[172:175], v[120:123], v[100:115]
	v_add_f32_e32 v72, v78, v136
	v_add_f32_e32 v72, v79, v72
	v_add_f32_e32 v72, v80, v72
	v_add_f32_e32 v136, v81, v72
	v_cvt_pk_bf16_f32 v72, v76, v77
	v_and_b32_e32 v144, v72, v196
	v_cvt_pk_bf16_f32 v72, v78, v79
	v_and_b32_e32 v145, v72, v196
	ds_read_b64_tr_b16 v[72:73], v197 offset:29696
	ds_read_b64_tr_b16 v[74:75], v197 offset:30208
	s_waitcnt lgkmcnt(12)
	v_mfma_f32_32x32x16_bf16 v[84:99], v[168:171], v[120:123], v[84:99]
	v_add_f32_e32 v76, v82, v136
	v_add_f32_e32 v76, v83, v76
	v_add_f32_e32 v76, v52, v76
	v_add_f32_e32 v136, v53, v76
	v_cvt_pk_bf16_f32 v76, v80, v81
	v_and_b32_e32 v146, v76, v196
	v_cvt_pk_bf16_f32 v76, v82, v83
	v_and_b32_e32 v147, v76, v196
	ds_read_b64_tr_b16 v[76:77], v197 offset:26624
	ds_read_b64_tr_b16 v[78:79], v197 offset:27136
	s_waitcnt lgkmcnt(13)
	v_mfma_f32_32x32x16_bf16 v[100:115], v[164:167], v[124:127], v[100:115]
	v_add_f32_e32 v80, v54, v136
	v_add_f32_e32 v80, v55, v80
	v_cvt_pk_bf16_f32 v52, v52, v53
	v_add_f32_e32 v80, v56, v80
	v_and_b32_e32 v140, v52, v196
	v_cvt_pk_bf16_f32 v52, v54, v55
	v_add_f32_e32 v80, v57, v80
	v_and_b32_e32 v141, v52, v196
	ds_read_b64_tr_b16 v[52:53], v197 offset:30720
	ds_read_b64_tr_b16 v[54:55], v197 offset:31232
	s_waitcnt lgkmcnt(14)
	v_mfma_f32_32x32x16_bf16 v[84:99], v[160:163], v[124:127], v[84:99]
	v_add_f32_e32 v80, v58, v80
	v_add_f32_e32 v80, v59, v80
	v_cvt_pk_bf16_f32 v56, v56, v57
	v_add_f32_e32 v80, v60, v80
	v_and_b32_e32 v142, v56, v196
	v_cvt_pk_bf16_f32 v56, v58, v59
	v_add_f32_e32 v80, v61, v80
	v_and_b32_e32 v143, v56, v196
	ds_read_b64_tr_b16 v[56:57], v197 offset:27648
	ds_read_b64_tr_b16 v[58:59], v197 offset:28160
	s_waitcnt lgkmcnt(14)
	v_mfma_f32_32x32x16_bf16 v[100:115], v[156:159], v[128:131], v[100:115]
	v_add_f32_e32 v80, v62, v80
	v_add_f32_e32 v80, v63, v80
	v_cvt_pk_bf16_f32 v60, v60, v61
	v_add_f32_e32 v80, v64, v80
	v_and_b32_e32 v136, v60, v196
	v_cvt_pk_bf16_f32 v60, v62, v63
	v_add_f32_e32 v80, v65, v80
	v_and_b32_e32 v137, v60, v196
	ds_read_b64_tr_b16 v[60:61], v197 offset:31744
	ds_read_b64_tr_b16 v[62:63], v197 offset:32256
	v_mfma_f32_32x32x16_bf16 v[84:99], v[152:155], v[128:131], v[84:99]
	v_add_f32_e32 v80, v66, v80
	v_cvt_pk_bf16_f32 v64, v64, v65
	v_add_f32_e32 v80, v67, v80
	v_and_b32_e32 v138, v64, v196
	v_cvt_pk_bf16_f32 v64, v66, v67
	v_add_f32_e32 v80, 0, v80
	v_and_b32_e32 v139, v64, v196
	s_mov_b32 s22, 0xfffe0000
	s_mov_b32 s23, -1
	v_lshl_add_u64 v[64:65], v[194:195], 0, s[22:23]
	s_add_i32 s10, s25, s46
	s_mov_b32 s11, m0
	s_mov_b32 m0, s10
	s_nop 0
	global_load_lds_dwordx4 v[64:65], off
	s_mov_b32 m0, s11
	v_lshl_add_u64 v[64:65], v[192:193], 0, s[22:23]
	s_add_i32 s10, s24, s47
	s_mov_b32 s11, m0
	s_mov_b32 m0, s10
	s_nop 0
	global_load_lds_dwordx4 v[64:65], off
	s_mov_b32 m0, s11
	v_and_b32_e32 v66, v80, v196
	v_add_f32_e32 v204, v220, v66
	s_mov_b64 s[10:11], 0

.LBB0_801:
	s_add_i32 s10, s24, 0x2000
	s_cmpk_lg_i32 s24, 0x4000
	v_alignbit_b32 v132, v133, v132, 1
	s_cselect_b32 s54, s10, 0
	v_bfe_i32 v196, v132, 0, 1
	v_add_u32_e32 v197, s25, v219
	ds_read_b64_tr_b16 v[152:153], v197 offset:24576
	ds_read_b64_tr_b16 v[154:155], v197 offset:25088
	s_waitcnt lgkmcnt(9)
	v_mfma_f32_32x32x16_bf16 v[68:83], v[64:67], v[116:119], v[36:51]
	v_add_f32_e32 v52, v100, v101
	v_add_f32_e32 v52, v102, v52
	v_add_f32_e32 v52, v103, v52
	v_cvt_pk_bf16_f32 v53, v100, v101
	v_add_f32_e32 v52, v104, v52
	v_and_b32_e32 v148, v53, v196
	v_cvt_pk_bf16_f32 v53, v102, v103
	v_add_f32_e32 v52, v105, v52
	v_and_b32_e32 v149, v53, v196
	ds_read_b64_tr_b16 v[156:157], v197 offset:28672
	ds_read_b64_tr_b16 v[158:159], v197 offset:29184
	v_add_f32_e32 v52, v106, v52
	v_add_f32_e32 v52, v107, v52
	v_add_f32_e32 v52, v108, v52
	v_add_f32_e32 v136, v109, v52
	s_waitcnt lgkmcnt(10)
	v_mfma_f32_32x32x16_bf16 v[52:67], v[180:183], v[116:119], v[36:51]
	v_cvt_pk_bf16_f32 v100, v104, v105
	v_and_b32_e32 v150, v100, v196
	v_cvt_pk_bf16_f32 v100, v106, v107
	v_and_b32_e32 v151, v100, v196
	ds_read_b64_tr_b16 v[100:101], v197 offset:25600
	ds_read_b64_tr_b16 v[102:103], v197 offset:26112
	s_waitcnt lgkmcnt(11)
	v_mfma_f32_32x32x16_bf16 v[68:83], v[184:187], v[120:123], v[68:83]
	v_add_f32_e32 v104, v110, v136
	v_add_f32_e32 v104, v111, v104
	v_add_f32_e32 v104, v112, v104
	v_add_f32_e32 v136, v113, v104
	v_cvt_pk_bf16_f32 v104, v108, v109
	v_and_b32_e32 v144, v104, v196
	v_cvt_pk_bf16_f32 v104, v110, v111
	v_and_b32_e32 v145, v104, v196
	ds_read_b64_tr_b16 v[104:105], v197 offset:29696
	ds_read_b64_tr_b16 v[106:107], v197 offset:30208
	s_waitcnt lgkmcnt(12)
	v_mfma_f32_32x32x16_bf16 v[52:67], v[176:179], v[120:123], v[52:67]
	v_add_f32_e32 v108, v114, v136
	v_add_f32_e32 v108, v115, v108
	v_add_f32_e32 v108, v84, v108
	v_add_f32_e32 v136, v85, v108
	v_cvt_pk_bf16_f32 v108, v112, v113
	v_and_b32_e32 v146, v108, v196
	v_cvt_pk_bf16_f32 v108, v114, v115
	v_and_b32_e32 v147, v108, v196
	ds_read_b64_tr_b16 v[108:109], v197 offset:26624
	ds_read_b64_tr_b16 v[110:111], v197 offset:27136
	s_waitcnt lgkmcnt(13)
	v_mfma_f32_32x32x16_bf16 v[68:83], v[172:175], v[124:127], v[68:83]
	v_add_f32_e32 v112, v86, v136
	v_add_f32_e32 v112, v87, v112
	v_cvt_pk_bf16_f32 v84, v84, v85
	v_add_f32_e32 v112, v88, v112
	v_and_b32_e32 v140, v84, v196
	v_cvt_pk_bf16_f32 v84, v86, v87
	v_add_f32_e32 v112, v89, v112
	v_and_b32_e32 v141, v84, v196
	ds_read_b64_tr_b16 v[84:85], v197 offset:30720
	ds_read_b64_tr_b16 v[86:87], v197 offset:31232
	s_waitcnt lgkmcnt(14)
	v_mfma_f32_32x32x16_bf16 v[52:67], v[168:171], v[124:127], v[52:67]
	v_add_f32_e32 v112, v90, v112
	v_add_f32_e32 v112, v91, v112
	v_cvt_pk_bf16_f32 v88, v88, v89
	v_add_f32_e32 v112, v92, v112
	v_and_b32_e32 v142, v88, v196
	v_cvt_pk_bf16_f32 v88, v90, v91
	v_add_f32_e32 v112, v93, v112
	v_and_b32_e32 v143, v88, v196
	ds_read_b64_tr_b16 v[88:89], v197 offset:27648
	ds_read_b64_tr_b16 v[90:91], v197 offset:28160
	s_waitcnt lgkmcnt(14)
	v_mfma_f32_32x32x16_bf16 v[68:83], v[164:167], v[128:131], v[68:83]
	v_add_f32_e32 v112, v94, v112
	v_add_f32_e32 v112, v95, v112
	v_cvt_pk_bf16_f32 v92, v92, v93
	v_add_f32_e32 v112, v96, v112
	v_and_b32_e32 v136, v92, v196
	v_cvt_pk_bf16_f32 v92, v94, v95
	v_add_f32_e32 v112, v97, v112
	v_and_b32_e32 v137, v92, v196
	ds_read_b64_tr_b16 v[92:93], v197 offset:31744
	ds_read_b64_tr_b16 v[94:95], v197 offset:32256
	v_mfma_f32_32x32x16_bf16 v[52:67], v[160:163], v[128:131], v[52:67]
	v_add_f32_e32 v112, v98, v112
	v_cvt_pk_bf16_f32 v96, v96, v97
	v_add_f32_e32 v112, v99, v112
	v_and_b32_e32 v138, v96, v196
	v_cvt_pk_bf16_f32 v96, v98, v99
	v_add_f32_e32 v112, 0, v112
	v_and_b32_e32 v139, v96, v196
	v_and_b32_e32 v96, v112, v196
	v_add_f32_e32 v220, v204, v96
	s_add_i32 s10, s24, s46
	s_mov_b32 s11, m0
	s_mov_b32 m0, s10
	s_nop 0
	global_load_lds_dwordx4 v[194:195], off
	s_mov_b32 m0, s11
	s_add_i32 s10, s54, s47
	s_mov_b32 s11, m0
	s_mov_b32 m0, s10
	s_nop 0
	global_load_lds_dwordx4 v[192:193], off
	s_mov_b32 m0, s11
	s_mov_b64 s[10:11], 0

.LBB0_804:
	s_add_i32 s0, s0, 2
	s_add_i32 s10, s54, 0x2000
	v_alignbit_b32 v84, v135, v134, 1
	v_alignbit_b32 v85, v134, v133, 1
	v_lshrrev_b32_e32 v86, 1, v135
	s_cmpk_lg_i32 s54, 0x4000
	v_alignbit_b32 v132, v85, v132, 1
	v_alignbit_b32 v133, v84, v85, 1
	v_alignbit_b32 v134, v86, v84, 1
	v_lshrrev_b32_e32 v135, 2, v135
	s_cselect_b32 s42, s10, 0
	v_lshl_add_u64 v[192:193], v[192:193], 0, s[80:81]
	s_cmp_ge_i32 s0, s1
	v_lshl_add_u64 v[194:195], v[194:195], 0, s[80:81]
	s_cbranch_scc1 .LBB0_813
	s_mov_b32 s10, s24
	s_mov_b32 s25, s54
	s_mov_b32 s24, s42
	s_branch .LBB0_798
.LBB0_812:
	v_mov_b64_e32 v[34:35], v[18:19]
	s_movk_i32 s42, 0x4000
	s_movk_i32 s54, 0x2000
	v_mov_b32_e32 v220, 0
	v_mov_b64_e32 v[32:33], v[16:17]
	v_mov_b64_e32 v[30:31], v[14:15]
	v_mov_b64_e32 v[28:29], v[12:13]
	v_mov_b64_e32 v[26:27], v[10:11]
	v_mov_b64_e32 v[24:25], v[8:9]
	v_mov_b64_e32 v[22:23], v[6:7]
	v_mov_b64_e32 v[20:21], v[4:5]

.LBB0_815:
	v_bfe_i32 v188, v132, 0, 1
	v_add_u32_e32 v189, s24, v219
	ds_read_b64_tr_b16 v[184:185], v189 offset:24576
	ds_read_b64_tr_b16 v[186:187], v189 offset:25088
	s_waitcnt lgkmcnt(9)
	v_mfma_f32_32x32x16_bf16 v[100:115], v[180:183], v[116:119], v[36:51]
	v_add_f32_e32 v84, v68, v69
	v_add_f32_e32 v84, v70, v84
	v_add_f32_e32 v84, v71, v84
	v_cvt_pk_bf16_f32 v68, v68, v69
	v_add_f32_e32 v84, v72, v84
	v_and_b32_e32 v148, v68, v188
	v_cvt_pk_bf16_f32 v68, v70, v71
	v_add_f32_e32 v84, v73, v84
	v_and_b32_e32 v149, v68, v188
	ds_read_b64_tr_b16 v[180:181], v189 offset:28672
	ds_read_b64_tr_b16 v[182:183], v189 offset:29184
	v_add_f32_e32 v68, v74, v84
	s_waitcnt lgkmcnt(10)
	v_mfma_f32_32x32x16_bf16 v[84:99], v[176:179], v[116:119], v[36:51]
	v_add_f32_e32 v68, v75, v68
	v_add_f32_e32 v68, v76, v68
	v_add_f32_e32 v136, v77, v68
	v_cvt_pk_bf16_f32 v68, v72, v73
	v_and_b32_e32 v150, v68, v188
	v_cvt_pk_bf16_f32 v68, v74, v75
	v_and_b32_e32 v151, v68, v188
	ds_read_b64_tr_b16 v[68:69], v189 offset:25600
	ds_read_b64_tr_b16 v[70:71], v189 offset:26112
	s_waitcnt lgkmcnt(11)
	v_mfma_f32_32x32x16_bf16 v[100:115], v[172:175], v[120:123], v[100:115]
	v_add_f32_e32 v72, v78, v136
	v_add_f32_e32 v72, v79, v72
	v_add_f32_e32 v72, v80, v72
	v_add_f32_e32 v136, v81, v72
	v_cvt_pk_bf16_f32 v72, v76, v77
	v_and_b32_e32 v144, v72, v188
	v_cvt_pk_bf16_f32 v72, v78, v79
	v_and_b32_e32 v145, v72, v188
	ds_read_b64_tr_b16 v[72:73], v189 offset:29696
	ds_read_b64_tr_b16 v[74:75], v189 offset:30208
	s_waitcnt lgkmcnt(12)
	v_mfma_f32_32x32x16_bf16 v[84:99], v[168:171], v[120:123], v[84:99]
	v_add_f32_e32 v76, v82, v136
	v_add_f32_e32 v76, v83, v76
	v_add_f32_e32 v76, v52, v76
	v_add_f32_e32 v136, v53, v76
	v_cvt_pk_bf16_f32 v76, v80, v81
	v_and_b32_e32 v146, v76, v188
	v_cvt_pk_bf16_f32 v76, v82, v83
	v_and_b32_e32 v147, v76, v188
	ds_read_b64_tr_b16 v[76:77], v189 offset:26624
	ds_read_b64_tr_b16 v[78:79], v189 offset:27136
	s_waitcnt lgkmcnt(13)
	v_mfma_f32_32x32x16_bf16 v[100:115], v[164:167], v[124:127], v[100:115]
	v_add_f32_e32 v80, v54, v136
	v_add_f32_e32 v80, v55, v80
	v_cvt_pk_bf16_f32 v52, v52, v53
	v_add_f32_e32 v80, v56, v80
	v_and_b32_e32 v140, v52, v188
	v_cvt_pk_bf16_f32 v52, v54, v55
	v_add_f32_e32 v80, v57, v80
	v_and_b32_e32 v141, v52, v188
	ds_read_b64_tr_b16 v[52:53], v189 offset:30720
	ds_read_b64_tr_b16 v[54:55], v189 offset:31232
	s_waitcnt lgkmcnt(14)
	v_mfma_f32_32x32x16_bf16 v[84:99], v[160:163], v[124:127], v[84:99]
	v_add_f32_e32 v80, v58, v80
	v_add_f32_e32 v80, v59, v80
	v_cvt_pk_bf16_f32 v56, v56, v57
	v_add_f32_e32 v80, v60, v80
	v_and_b32_e32 v142, v56, v188
	v_cvt_pk_bf16_f32 v56, v58, v59
	v_add_f32_e32 v80, v61, v80
	v_and_b32_e32 v143, v56, v188
	ds_read_b64_tr_b16 v[56:57], v189 offset:27648
	ds_read_b64_tr_b16 v[58:59], v189 offset:28160
	s_waitcnt lgkmcnt(14)
	v_mfma_f32_32x32x16_bf16 v[100:115], v[156:159], v[128:131], v[100:115]
	v_add_f32_e32 v80, v62, v80
	v_add_f32_e32 v80, v63, v80
	v_cvt_pk_bf16_f32 v60, v60, v61
	v_add_f32_e32 v80, v64, v80
	v_and_b32_e32 v136, v60, v188
	v_cvt_pk_bf16_f32 v60, v62, v63
	v_add_f32_e32 v80, v65, v80
	v_and_b32_e32 v137, v60, v188
	ds_read_b64_tr_b16 v[60:61], v189 offset:31744
	ds_read_b64_tr_b16 v[62:63], v189 offset:32256
	v_mfma_f32_32x32x16_bf16 v[84:99], v[152:155], v[128:131], v[84:99]
	v_add_f32_e32 v80, v66, v80
	v_cvt_pk_bf16_f32 v64, v64, v65
	v_add_f32_e32 v80, v67, v80
	v_and_b32_e32 v138, v64, v188
	v_cvt_pk_bf16_f32 v64, v66, v67
	v_add_f32_e32 v80, 0, v80
	v_and_b32_e32 v139, v64, v188
	s_add_i32 s0, s25, 1
	s_cmp_ge_u32 s0, s48
	s_cselect_b64 s[10:11], -1, 0
	s_and_b64 vcc, exec, s[10:11]
	s_cbranch_vccnz .LBB0_817
	s_mov_b32 s22, 0xfffe0000
	s_mov_b32 s23, -1
	s_add_i32 s0, s54, s46
	v_lshl_add_u64 v[64:65], v[206:207], 0, s[22:23]
	s_mov_b32 s1, m0
	s_mov_b32 m0, s0
	s_nop 0
	global_load_lds_dwordx4 v[64:65], off
	s_mov_b32 m0, s1

.LBB0_819:
	v_and_b32_e32 v64, v80, v188
	v_add_f32_e32 v202, v220, v64
	s_mov_b64 s[0:1], 0

.LBB0_830:
	v_and_b32_e32 v96, v108, v203
	v_add_f32_e32 v220, v202, v96
	s_mov_b64 s[24:25], 0

.LBB0_856:
	s_waitcnt vmcnt(2) lgkmcnt(0)
	s_barrier
	s_andn2_b64 vcc, exec, s[24:25]
	s_cbranch_vccz .LBB0_842
	s_branch .LBB0_843
.LBB0_863:
	s_mov_b32 s42, s24

.LBB0_907:
	v_add_f32_e32 v203, v248, v80
	s_mov_b64 s[26:27], 0

.LBB0_918:
	v_add_f32_e32 v248, v203, v92
	s_mov_b64 s[30:31], 0

.LBB0_944:
	s_waitcnt vmcnt(2) lgkmcnt(0)
	s_barrier
	s_andn2_b64 vcc, exec, s[30:31]
	s_cbranch_vccz .LBB0_930
	s_branch .LBB0_931
.LBB0_951:
	s_mov_b32 s25, 5
	s_mov_b32 s30, 0
	s_movk_i32 s31, 0x4000
	s_movk_i32 s28, 0x2000
	s_add_i32 s0, s25, 5
	s_cmp_ge_i32 s0, s51
	v_lshlrev_b32_e32 v192, 4, v219
	s_cbranch_scc1 .LBB0_900

.LBB0_953:
	v_add_u32_e32 v188, s28, v247
	ds_read_b64_tr_b16 v[180:181], v188 offset:24576
	ds_read_b64_tr_b16 v[182:183], v188 offset:25088
	s_waitcnt lgkmcnt(9)
	v_mfma_f32_32x32x16_bf16 v[100:115], v[176:179], v[116:119], v[36:51]
	v_add_f32_e32 v84, v68, v69
	v_add_f32_e32 v84, v70, v84
	v_add_f32_e32 v84, v71, v84
	v_add_f32_e32 v84, v72, v84
	v_add_f32_e32 v84, v73, v84
	v_cvt_pk_bf16_f32 v144, v68, v69
	v_cvt_pk_bf16_f32 v145, v70, v71
	ds_read_b64_tr_b16 v[176:177], v188 offset:28672
	ds_read_b64_tr_b16 v[178:179], v188 offset:29184
	v_add_f32_e32 v68, v74, v84
	s_waitcnt lgkmcnt(10)
	v_mfma_f32_32x32x16_bf16 v[84:99], v[168:171], v[116:119], v[36:51]
	v_add_f32_e32 v68, v75, v68
	v_add_f32_e32 v68, v76, v68
	v_add_f32_e32 v132, v77, v68
	v_cvt_pk_bf16_f32 v146, v72, v73
	v_cvt_pk_bf16_f32 v147, v74, v75
	ds_read_b64_tr_b16 v[68:69], v188 offset:25600
	ds_read_b64_tr_b16 v[70:71], v188 offset:26112
	s_waitcnt lgkmcnt(11)
	v_mfma_f32_32x32x16_bf16 v[100:115], v[172:175], v[120:123], v[100:115]
	v_add_f32_e32 v72, v78, v132
	v_add_f32_e32 v72, v79, v72
	v_add_f32_e32 v72, v80, v72
	v_add_f32_e32 v132, v81, v72
	v_cvt_pk_bf16_f32 v140, v76, v77
	v_cvt_pk_bf16_f32 v141, v78, v79
	ds_read_b64_tr_b16 v[72:73], v188 offset:29696
	ds_read_b64_tr_b16 v[74:75], v188 offset:30208
	s_waitcnt lgkmcnt(12)
	v_mfma_f32_32x32x16_bf16 v[84:99], v[164:167], v[120:123], v[84:99]
	v_add_f32_e32 v76, v82, v132
	v_add_f32_e32 v76, v83, v76
	v_add_f32_e32 v76, v52, v76
	v_add_f32_e32 v132, v53, v76
	v_cvt_pk_bf16_f32 v142, v80, v81
	v_cvt_pk_bf16_f32 v143, v82, v83
	ds_read_b64_tr_b16 v[76:77], v188 offset:26624
	ds_read_b64_tr_b16 v[78:79], v188 offset:27136
	s_waitcnt lgkmcnt(13)
	v_mfma_f32_32x32x16_bf16 v[100:115], v[160:163], v[124:127], v[100:115]
	v_add_f32_e32 v80, v54, v132
	v_add_f32_e32 v80, v55, v80
	v_add_f32_e32 v80, v56, v80
	v_add_f32_e32 v80, v57, v80
	v_cvt_pk_bf16_f32 v136, v52, v53
	v_cvt_pk_bf16_f32 v137, v54, v55
	ds_read_b64_tr_b16 v[52:53], v188 offset:30720
	ds_read_b64_tr_b16 v[54:55], v188 offset:31232
	s_waitcnt lgkmcnt(14)
	v_mfma_f32_32x32x16_bf16 v[84:99], v[156:159], v[124:127], v[84:99]
	v_add_f32_e32 v80, v58, v80
	v_add_f32_e32 v80, v59, v80
	v_add_f32_e32 v80, v60, v80
	v_add_f32_e32 v80, v61, v80
	v_cvt_pk_bf16_f32 v138, v56, v57
	v_cvt_pk_bf16_f32 v139, v58, v59
	ds_read_b64_tr_b16 v[56:57], v188 offset:27648
	ds_read_b64_tr_b16 v[58:59], v188 offset:28160
	s_waitcnt lgkmcnt(14)
	v_mfma_f32_32x32x16_bf16 v[100:115], v[152:155], v[128:131], v[100:115]
	v_add_f32_e32 v80, v62, v80
	v_add_f32_e32 v80, v63, v80
	v_add_f32_e32 v80, v64, v80
	v_add_f32_e32 v80, v65, v80
	v_cvt_pk_bf16_f32 v132, v60, v61
	v_cvt_pk_bf16_f32 v133, v62, v63
	ds_read_b64_tr_b16 v[60:61], v188 offset:31744
	ds_read_b64_tr_b16 v[62:63], v188 offset:32256
	v_mfma_f32_32x32x16_bf16 v[84:99], v[148:151], v[128:131], v[84:99]
	v_add_f32_e32 v80, v66, v80
	v_add_f32_e32 v80, v67, v80
	v_add_f32_e32 v80, 0, v80
	v_cvt_pk_bf16_f32 v134, v64, v65
	v_cvt_pk_bf16_f32 v135, v66, v67
	v_lshl_add_u64 v[188:189], v[184:185], 0, s[0:1]
	v_lshl_add_u64 v[64:65], v[188:189], 0, s[54:55]
	s_add_i32 s26, s31, s49
	s_mov_b32 s27, m0
	s_mov_b32 m0, s26
	s_nop 0
	global_load_lds_dwordx4 v[64:65], off
	s_mov_b32 m0, s27
	v_lshl_add_u64 v[190:191], v[186:187], 0, s[0:1]
	s_mov_b64 s[26:27], 0x10000
	v_lshl_add_u64 v[64:65], v[190:191], 0, s[26:27]
	s_add_i32 s26, s30, s50
	s_mov_b32 s27, m0
	s_mov_b32 m0, s26
	s_nop 0
	global_load_lds_dwordx4 v[64:65], off
	s_mov_b32 m0, s27
	v_add_f32_e32 v195, v248, v80
	s_mov_b64 s[26:27], 0

.LBB0_956:
	s_add_i32 s26, s30, 0x2000
	s_cmpk_lg_i32 s30, 0x4000
	s_cselect_b32 s53, s26, 0
	v_add_u32_e32 v196, s31, v247
	ds_read_b64_tr_b16 v[152:153], v196 offset:24576
	ds_read_b64_tr_b16 v[154:155], v196 offset:25088
	s_waitcnt lgkmcnt(9)
	v_mfma_f32_32x32x16_bf16 v[68:83], v[64:67], v[116:119], v[36:51]
	v_add_f32_e32 v52, v100, v101
	v_add_f32_e32 v52, v102, v52
	v_add_f32_e32 v52, v103, v52
	v_add_f32_e32 v52, v104, v52
	v_add_f32_e32 v52, v105, v52
	v_cvt_pk_bf16_f32 v144, v100, v101
	v_cvt_pk_bf16_f32 v145, v102, v103
	ds_read_b64_tr_b16 v[148:149], v196 offset:28672
	ds_read_b64_tr_b16 v[150:151], v196 offset:29184
	v_add_f32_e32 v52, v106, v52
	v_add_f32_e32 v52, v107, v52
	v_add_f32_e32 v52, v108, v52
	v_add_f32_e32 v132, v109, v52
	s_waitcnt lgkmcnt(10)
	v_mfma_f32_32x32x16_bf16 v[52:67], v[176:179], v[116:119], v[36:51]
	v_cvt_pk_bf16_f32 v146, v104, v105
	v_cvt_pk_bf16_f32 v147, v106, v107
	ds_read_b64_tr_b16 v[100:101], v196 offset:25600
	ds_read_b64_tr_b16 v[102:103], v196 offset:26112
	s_waitcnt lgkmcnt(11)
	v_mfma_f32_32x32x16_bf16 v[68:83], v[180:183], v[120:123], v[68:83]
	v_add_f32_e32 v104, v110, v132
	v_add_f32_e32 v104, v111, v104
	v_add_f32_e32 v104, v112, v104
	v_add_f32_e32 v132, v113, v104
	v_cvt_pk_bf16_f32 v140, v108, v109
	v_cvt_pk_bf16_f32 v141, v110, v111
	ds_read_b64_tr_b16 v[104:105], v196 offset:29696
	ds_read_b64_tr_b16 v[106:107], v196 offset:30208
	s_waitcnt lgkmcnt(12)
	v_mfma_f32_32x32x16_bf16 v[52:67], v[172:175], v[120:123], v[52:67]
	v_add_f32_e32 v108, v114, v132
	v_add_f32_e32 v108, v115, v108
	v_add_f32_e32 v108, v84, v108
	v_add_f32_e32 v132, v85, v108
	v_cvt_pk_bf16_f32 v142, v112, v113
	v_cvt_pk_bf16_f32 v143, v114, v115
	ds_read_b64_tr_b16 v[108:109], v196 offset:26624
	ds_read_b64_tr_b16 v[110:111], v196 offset:27136
	s_waitcnt lgkmcnt(13)
	v_mfma_f32_32x32x16_bf16 v[68:83], v[168:171], v[124:127], v[68:83]
	v_add_f32_e32 v112, v86, v132
	v_add_f32_e32 v112, v87, v112
	v_add_f32_e32 v112, v88, v112
	v_add_f32_e32 v112, v89, v112
	v_cvt_pk_bf16_f32 v136, v84, v85
	v_cvt_pk_bf16_f32 v137, v86, v87
	ds_read_b64_tr_b16 v[84:85], v196 offset:30720
	ds_read_b64_tr_b16 v[86:87], v196 offset:31232
	s_waitcnt lgkmcnt(14)
	v_mfma_f32_32x32x16_bf16 v[52:67], v[164:167], v[124:127], v[52:67]
	v_add_f32_e32 v112, v90, v112
	v_add_f32_e32 v112, v91, v112
	v_add_f32_e32 v112, v92, v112
	v_add_f32_e32 v112, v93, v112
	v_cvt_pk_bf16_f32 v138, v88, v89
	v_cvt_pk_bf16_f32 v139, v90, v91
	ds_read_b64_tr_b16 v[88:89], v196 offset:27648
	ds_read_b64_tr_b16 v[90:91], v196 offset:28160
	s_waitcnt lgkmcnt(14)
	v_mfma_f32_32x32x16_bf16 v[68:83], v[160:163], v[128:131], v[68:83]
	v_add_f32_e32 v112, v94, v112
	v_add_f32_e32 v112, v95, v112
	v_add_f32_e32 v112, v96, v112
	v_add_f32_e32 v112, v97, v112
	v_cvt_pk_bf16_f32 v132, v92, v93
	v_cvt_pk_bf16_f32 v133, v94, v95
	ds_read_b64_tr_b16 v[92:93], v196 offset:31744
	ds_read_b64_tr_b16 v[94:95], v196 offset:32256
	v_mfma_f32_32x32x16_bf16 v[52:67], v[156:159], v[128:131], v[52:67]
	v_add_f32_e32 v112, v98, v112
	v_add_f32_e32 v112, v99, v112
	v_add_f32_e32 v112, 0, v112
	v_cvt_pk_bf16_f32 v134, v96, v97
	v_cvt_pk_bf16_f32 v135, v98, v99
	v_lshl_add_u64 v[96:97], v[188:189], 0, s[80:81]
	s_add_i32 s26, s30, s49
	s_mov_b32 s27, m0
	s_mov_b32 m0, s26
	s_nop 0
	global_load_lds_dwordx4 v[96:97], off
	s_mov_b32 m0, s27
	s_mov_b64 s[26:27], 0x20000
	v_lshl_add_u64 v[96:97], v[190:191], 0, s[26:27]
	s_add_i32 s26, s53, s50
	s_mov_b32 s27, m0
	s_mov_b32 m0, s26
	s_nop 0
	global_load_lds_dwordx4 v[96:97], off
	s_mov_b32 m0, s27
	v_add_f32_e32 v248, v195, v112
	s_mov_b64 s[26:27], 0

.LBB0_959:
	s_add_i32 s26, s25, 2
	s_add_i32 s27, s53, 0x2000
	s_cmpk_lg_i32 s53, 0x4000
	s_cselect_b32 s54, s27, 0
	s_add_i32 s25, s25, 7
	s_mov_b64 s[28:29], 0x20000
	v_lshl_add_u64 v[186:187], v[186:187], 0, s[28:29]
	s_cmp_ge_i32 s25, s51
	v_lshl_add_u64 v[184:185], v[184:185], 0, s[28:29]
	s_mov_b32 s28, s30
	s_cbranch_scc1 .LBB0_901
	s_mov_b32 s31, s53
	s_mov_b32 s30, s54
	s_mov_b32 s25, s26
	s_mov_b64 s[54:55], 0x30000
	s_branch .LBB0_953
.LBB0_967:
	s_mov_b32 s54, s28
